# in-proj quad epilogue: LDS-DMA stage issued after the bias load, counted vmcnt(6) instead of vmcnt(0) (on stagger0+S1+PTfill)
# baseline (speedup 1.0000x reference)
.LBB0_236:
	s_add_i32 s98, s18, 0x2080
	v_mov_b32_e32 v172, v1
	v_mov_b32_e32 v224, v227
	s_lshl_b32 s4, s56, 8
	s_lshl_b32 s18, s55, 8
	s_add_i32 s4, s4, s39
	v_lshlrev_b32_e32 v132, 3, v224
	s_or_b32 s18, s18, s37
	v_lshl_add_u32 v225, v172, 3, s4
	s_add_i32 s4, s55, -2
	v_add_u32_e32 v130, s18, v132
	s_cmp_lt_u32 s4, 16
	s_mov_b64 s[18:19], -1
	v_ashrrev_i32_e32 v131, 31, v130
	s_cbranch_scc1 .LBB0_239
	s_mov_b32 s99, s4
	s_mov_b32 s4, s70
	s_mov_b32 m0, s38
	s_nop 0
	buffer_load_dwordx4 v207, s[4:7], s98 offen lds
	s_mov_b32 m0, s41
	s_nop 0
	buffer_load_dwordx4 v209, s[4:7], s98 offen lds
	s_mov_b32 s4, s99
	v_lshl_add_u64 v[134:135], v[130:131], 2, s[12:13]
	global_load_dwordx4 v[138:141], v[134:135], off
	global_load_dwordx4 v[142:145], v[134:135], off offset:16
	v_ashrrev_i32_e32 v146, 4, v130
	v_and_b32_e32 v136, 8, v132
	v_ashrrev_i32_e32 v132, 4, v225
	v_ashrrev_i32_e32 v147, 31, v146
	v_ashrrev_i32_e32 v133, 31, v132
	v_lshlrev_b64 v[146:147], 12, v[146:147]
	v_mov_b64_e32 v[134:135], s[72:73]
	v_lshlrev_b32_e32 v148, 8, v172
	v_lshl_add_u64 v[146:147], v[146:147], 0, v[132:133]
	v_and_b32_e32 v194, 0x100, v148
	v_mad_u64_u32 v[148:149], s[18:19], v146, s50, v[134:135]
	v_mad_i32_i24 v149, v147, s50, v149
	v_mov_b32_e32 v137, v195
	v_lshlrev_b32_e32 v136, 1, v136
	v_lshl_add_u64 v[146:147], v[148:149], 0, v[194:195]
	v_lshl_add_u64 v[146:147], v[146:147], 0, v[136:137]
	s_waitcnt vmcnt(1)
	v_pk_add_f32 v[148:149], v[116:117], v[140:141]
	v_pk_add_f32 v[150:151], v[114:115], v[138:139]
	s_waitcnt vmcnt(0)
	v_pk_add_f32 v[152:153], v[112:113], v[144:145]
	v_pk_add_f32 v[154:155], v[110:111], v[142:143]
	v_pk_add_f32 v[156:157], v[108:109], v[140:141]
	v_pk_add_f32 v[158:159], v[106:107], v[138:139]
	v_pk_add_f32 v[164:165], v[100:101], v[140:141]
	v_pk_add_f32 v[166:167], v[98:99], v[138:139]
	v_pk_add_f32 v[174:175], v[92:93], v[140:141]
	v_pk_add_f32 v[176:177], v[90:91], v[138:139]
	v_pk_add_f32 v[182:183], v[80:81], v[140:141]
	v_pk_add_f32 v[184:185], v[78:79], v[138:139]
	v_pk_add_f32 v[190:191], v[44:45], v[140:141]
	v_pk_add_f32 v[192:193], v[42:43], v[138:139]
	v_pk_add_f32 v[234:235], v[36:37], v[140:141]
	v_pk_add_f32 v[236:237], v[34:35], v[138:139]
	v_pk_add_f32 v[242:243], v[28:29], v[140:141]
	v_pk_add_f32 v[244:245], v[26:27], v[138:139]
	v_cvt_pk_bf16_f32 v138, v150, v151
	v_cvt_pk_bf16_f32 v139, v148, v149
	v_cvt_pk_bf16_f32 v140, v154, v155
	v_cvt_pk_bf16_f32 v141, v152, v153
	v_pk_add_f32 v[160:161], v[104:105], v[144:145]
	v_pk_add_f32 v[162:163], v[102:103], v[142:143]
	global_store_dwordx4 v[146:147], v[138:141], off
	v_pk_add_f32 v[168:169], v[96:97], v[144:145]
	v_pk_add_f32 v[170:171], v[94:95], v[142:143]
	v_cvt_pk_bf16_f32 v138, v158, v159
	v_cvt_pk_bf16_f32 v139, v156, v157
	v_cvt_pk_bf16_f32 v140, v162, v163
	v_cvt_pk_bf16_f32 v141, v160, v161
	global_store_dwordx4 v[146:147], v[138:141], off offset:32
	v_pk_add_f32 v[178:179], v[88:89], v[144:145]
	v_pk_add_f32 v[180:181], v[86:87], v[142:143]
	v_cvt_pk_bf16_f32 v138, v166, v167
	v_cvt_pk_bf16_f32 v139, v164, v165
	v_cvt_pk_bf16_f32 v140, v170, v171
	v_cvt_pk_bf16_f32 v141, v168, v169
	global_store_dwordx4 v[146:147], v[138:141], off offset:64
	v_pk_add_f32 v[186:187], v[48:49], v[144:145]
	v_pk_add_f32 v[188:189], v[46:47], v[142:143]
	v_cvt_pk_bf16_f32 v138, v176, v177
	v_cvt_pk_bf16_f32 v139, v174, v175
	v_cvt_pk_bf16_f32 v140, v180, v181
	v_cvt_pk_bf16_f32 v141, v178, v179
	global_store_dwordx4 v[146:147], v[138:141], off offset:96
	v_pk_add_f32 v[228:229], v[40:41], v[144:145]
	v_pk_add_f32 v[230:231], v[38:39], v[142:143]
	v_cvt_pk_bf16_f32 v138, v184, v185
	v_cvt_pk_bf16_f32 v139, v182, v183
	v_cvt_pk_bf16_f32 v140, v188, v189
	v_cvt_pk_bf16_f32 v141, v186, v187
	global_store_dwordx4 v[146:147], v[138:141], off offset:128
	v_pk_add_f32 v[238:239], v[32:33], v[144:145]
	v_pk_add_f32 v[240:241], v[30:31], v[142:143]
	v_cvt_pk_bf16_f32 v138, v192, v193
	v_cvt_pk_bf16_f32 v139, v190, v191
	v_cvt_pk_bf16_f32 v140, v230, v231
	v_cvt_pk_bf16_f32 v141, v228, v229
	global_store_dwordx4 v[146:147], v[138:141], off offset:160
	v_pk_add_f32 v[144:145], v[24:25], v[144:145]
	v_pk_add_f32 v[142:143], v[22:23], v[142:143]
	v_cvt_pk_bf16_f32 v138, v236, v237
	v_cvt_pk_bf16_f32 v139, v234, v235
	v_cvt_pk_bf16_f32 v140, v240, v241
	v_cvt_pk_bf16_f32 v141, v238, v239
	global_store_dwordx4 v[146:147], v[138:141], off offset:192
	s_nop 1
	v_cvt_pk_bf16_f32 v138, v244, v245
	v_cvt_pk_bf16_f32 v139, v242, v243
	v_cvt_pk_bf16_f32 v140, v142, v143
	v_cvt_pk_bf16_f32 v141, v144, v145
	global_store_dwordx4 v[146:147], v[138:141], off offset:224
	v_add_u32_e32 v146, 0x80, v130
	v_ashrrev_i32_e32 v147, 31, v146
	v_lshl_add_u64 v[142:143], v[146:147], 2, s[12:13]
	global_load_dwordx4 v[138:141], v[142:143], off
	s_nop 0
	global_load_dwordx4 v[142:145], v[142:143], off offset:16
	v_ashrrev_i32_e32 v146, 4, v146
	v_ashrrev_i32_e32 v147, 31, v146
	v_lshlrev_b64 v[146:147], 12, v[146:147]
	v_lshl_add_u64 v[132:133], v[146:147], 0, v[132:133]
	v_mad_u64_u32 v[134:135], s[18:19], v132, s50, v[134:135]
	v_mad_i32_i24 v135, v133, s50, v135
	v_lshl_add_u64 v[132:133], v[134:135], 0, v[194:195]
	v_lshl_add_u64 v[136:137], v[132:133], 0, v[136:137]
	s_waitcnt vmcnt(1)
	v_pk_add_f32 v[134:135], v[84:85], v[140:141]
	v_pk_add_f32 v[132:133], v[82:83], v[138:139]
	s_waitcnt vmcnt(0)
	v_pk_add_f32 v[146:147], v[76:77], v[144:145]
	v_pk_add_f32 v[148:149], v[74:75], v[142:143]
	v_cvt_pk_bf16_f32 v132, v132, v133
	v_cvt_pk_bf16_f32 v133, v134, v135
	v_pk_add_f32 v[150:151], v[72:73], v[140:141]
	v_cvt_pk_bf16_f32 v134, v148, v149
	v_cvt_pk_bf16_f32 v135, v146, v147
	v_pk_add_f32 v[152:153], v[70:71], v[138:139]
	v_pk_add_f32 v[154:155], v[68:69], v[144:145]
	v_pk_add_f32 v[156:157], v[66:67], v[142:143]
	global_store_dwordx4 v[136:137], v[132:135], off
	v_pk_add_f32 v[158:159], v[64:65], v[140:141]
	v_pk_add_f32 v[160:161], v[62:63], v[138:139]
	v_cvt_pk_bf16_f32 v132, v152, v153
	v_cvt_pk_bf16_f32 v133, v150, v151
	v_cvt_pk_bf16_f32 v134, v156, v157
	v_cvt_pk_bf16_f32 v135, v154, v155
	v_pk_add_f32 v[162:163], v[60:61], v[144:145]
	v_pk_add_f32 v[164:165], v[58:59], v[142:143]
	global_store_dwordx4 v[136:137], v[132:135], off offset:32
	v_pk_add_f32 v[166:167], v[56:57], v[140:141]
	v_pk_add_f32 v[168:169], v[54:55], v[138:139]
	v_cvt_pk_bf16_f32 v132, v160, v161
	v_cvt_pk_bf16_f32 v133, v158, v159
	v_cvt_pk_bf16_f32 v134, v164, v165
	v_cvt_pk_bf16_f32 v135, v162, v163
	v_pk_add_f32 v[170:171], v[52:53], v[144:145]
	v_pk_add_f32 v[174:175], v[50:51], v[142:143]
	global_store_dwordx4 v[136:137], v[132:135], off offset:64
	v_pk_add_f32 v[176:177], v[20:21], v[140:141]
	v_pk_add_f32 v[178:179], v[18:19], v[138:139]
	v_cvt_pk_bf16_f32 v132, v168, v169
	v_cvt_pk_bf16_f32 v133, v166, v167
	v_cvt_pk_bf16_f32 v134, v174, v175
	v_cvt_pk_bf16_f32 v135, v170, v171
	v_pk_add_f32 v[180:181], v[16:17], v[144:145]
	v_pk_add_f32 v[182:183], v[14:15], v[142:143]
	global_store_dwordx4 v[136:137], v[132:135], off offset:96
	v_pk_add_f32 v[184:185], v[12:13], v[140:141]
	v_pk_add_f32 v[186:187], v[10:11], v[138:139]
	v_cvt_pk_bf16_f32 v132, v178, v179
	v_cvt_pk_bf16_f32 v133, v176, v177
	v_cvt_pk_bf16_f32 v134, v182, v183
	v_cvt_pk_bf16_f32 v135, v180, v181
	v_pk_add_f32 v[188:189], v[8:9], v[144:145]
	v_pk_add_f32 v[190:191], v[6:7], v[142:143]
	global_store_dwordx4 v[136:137], v[132:135], off offset:128
	v_pk_add_f32 v[192:193], v[4:5], v[140:141]
	v_pk_add_f32 v[228:229], v[2:3], v[138:139]
	v_cvt_pk_bf16_f32 v132, v186, v187
	v_cvt_pk_bf16_f32 v133, v184, v185
	v_cvt_pk_bf16_f32 v134, v190, v191
	v_cvt_pk_bf16_f32 v135, v188, v189
	v_pk_add_f32 v[230:231], v[128:129], v[144:145]
	v_pk_add_f32 v[234:235], v[126:127], v[142:143]
	global_store_dwordx4 v[136:137], v[132:135], off offset:160
	v_pk_add_f32 v[140:141], v[124:125], v[140:141]
	v_pk_add_f32 v[138:139], v[122:123], v[138:139]
	v_cvt_pk_bf16_f32 v132, v228, v229
	v_cvt_pk_bf16_f32 v133, v192, v193
	v_cvt_pk_bf16_f32 v134, v234, v235
	v_cvt_pk_bf16_f32 v135, v230, v231
	v_pk_add_f32 v[144:145], v[120:121], v[144:145]
	v_pk_add_f32 v[142:143], v[118:119], v[142:143]
	global_store_dwordx4 v[136:137], v[132:135], off offset:192
	s_nop 1
	v_cvt_pk_bf16_f32 v132, v138, v139
	v_cvt_pk_bf16_f32 v133, v140, v141
	v_cvt_pk_bf16_f32 v134, v142, v143
	v_cvt_pk_bf16_f32 v135, v144, v145
	global_store_dwordx4 v[136:137], v[132:135], off offset:224
	s_cbranch_execz .LBB0_240

.LBB0_240:
	v_lshl_add_u64 v[130:131], v[130:131], 2, s[12:13]
	global_load_dwordx4 v[130:133], v[130:131], off offset:528
	s_mov_b32 s99, s4
	s_mov_b32 s4, s70
	s_mov_b32 m0, s38
	s_nop 0
	buffer_load_dwordx4 v207, s[4:7], s98 offen lds
	s_mov_b32 m0, s41
	s_nop 0
	buffer_load_dwordx4 v209, s[4:7], s98 offen lds
	s_mov_b32 s4, s99
	s_lshl_b32 s18, s4, 6
	s_or_b32 s33, s18, s40
	v_lshlrev_b32_e32 v194, 2, v224
	s_mulk_i32 s4, 0x300
	v_add_u32_e32 v176, s33, v194
	s_add_i32 s4, s42, s4
	v_lshl_add_u32 v134, v224, 4, s4
	v_lshl_add_u32 v150, v176, 2, 0
	ds_read_b128 v[138:141], v134
	ds_read_b128 v[162:165], v134 offset:256
	v_add_u32_e32 v135, 0x23100, v150
	ds_read_b128 v[166:169], v134 offset:512
	ds_read_b128 v[134:137], v135
	v_add_u32_e32 v142, 0x24100, v150
	v_add_u32_e32 v146, 0x25100, v150
	v_add_u32_e32 v150, 0x26100, v150
	ds_read_b128 v[142:145], v142
	ds_read_b128 v[146:149], v146
	ds_read_b128 v[150:153], v150
	s_waitcnt lgkmcnt(5)
	v_pk_add_f32 v[154:155], v[32:33], v[164:165]
	v_pk_add_f32 v[158:159], v[30:31], v[162:163]
	s_waitcnt lgkmcnt(4)
	v_pk_add_f32 v[156:157], v[4:5], v[168:169]
	v_pk_add_f32 v[160:161], v[2:3], v[166:167]
	v_pk_mul_f32 v[156:157], v[154:155], v[156:157]
	v_pk_mul_f32 v[154:155], v[158:159], v[160:161]
	v_pk_add_f32 v[158:159], v[24:25], v[164:165]
	v_pk_add_f32 v[170:171], v[22:23], v[162:163]
	v_pk_add_f32 v[160:161], v[124:125], v[168:169]
	v_pk_add_f32 v[174:175], v[122:123], v[166:167]
	v_pk_mul_f32 v[160:161], v[158:159], v[160:161]
	v_pk_mul_f32 v[158:159], v[170:171], v[174:175]
	v_mov_b32_e32 v178, 0
	v_mov_b32_e32 v170, 0
	v_mov_b32_e32 v179, 0
	v_mov_b32_e32 v171, 0
	v_mov_b32_e32 v180, 0
	v_mov_b32_e32 v182, 0
	v_mov_b32_e32 v181, v195
	v_mov_b32_e32 v183, 0
	v_mov_b32_dpp v178, v158 row_shr:1 row_mask:0xf bank_mask:0xf
	v_mov_b32_dpp v170, v154 row_shr:1 row_mask:0xf bank_mask:0xf
	v_mov_b32_dpp v179, v159 row_shr:1 row_mask:0xf bank_mask:0xf
	v_mov_b32_dpp v171, v155 row_shr:1 row_mask:0xf bank_mask:0xf
	v_mov_b32_dpp v180, v160 row_shr:1 row_mask:0xf bank_mask:0xf
	v_mov_b32_dpp v182, v156 row_shr:1 row_mask:0xf bank_mask:0xf
	v_mov_b32_dpp v181, v161 row_shr:1 row_mask:0xf bank_mask:0xf
	v_mov_b32_dpp v183, v157 row_shr:1 row_mask:0xf bank_mask:0xf
	v_cmp_ne_u32_e32 vcc, 15, v172
	v_ashrrev_i32_e32 v177, 31, v176
	s_and_saveexec_b64 s[18:19], vcc
	s_xor_b64 s[18:19], exec, s[18:19]
	s_or_saveexec_b64 s[18:19], s[18:19]
	v_ashrrev_i32_e32 v174, 7, v225
	v_ashrrev_i32_e32 v175, 31, v174
	v_lshlrev_b64 v[184:185], 13, v[174:175]
	s_xor_b64 exec, exec, s[18:19]
	s_cbranch_execz .LBB0_242
	v_lshl_add_u64 v[174:175], s[64:65], 0, v[184:185]
	v_lshl_add_u64 v[174:175], v[176:177], 2, v[174:175]
	global_store_dwordx4 v[174:175], v[154:157], off
	v_add_co_u32_e32 v174, vcc, 0x1000, v174
	s_nop 1
	v_addc_co_u32_e32 v175, vcc, 0, v175, vcc
	global_store_dwordx4 v[174:175], v[158:161], off

.LBB0_246:
	s_or_b64 exec, exec, s[18:19]
	s_waitcnt vmcnt(6)
	v_pk_add_f32 v[174:175], v[74:75], v[130:131]
	v_pk_add_f32 v[176:177], v[76:77], v[132:133]
	v_exp_f32_e32 v174, v174
	v_exp_f32_e32 v175, v175
	v_exp_f32_e32 v176, v176
	v_pk_add_f32 v[180:181], v[94:95], v[162:163]
	v_fmamk_f32 v174, v174, 0x3b808081, v223
	v_rcp_f32_e32 v174, v174
	v_fmamk_f32 v175, v175, 0x3b808081, v223
	v_rcp_f32_e32 v175, v175
	v_fmamk_f32 v176, v176, 0x3b808081, v223
	v_rcp_f32_e32 v176, v176
	v_pk_add_f32 v[184:185], v[62:63], v[166:167]
	v_rndne_f32_e32 v174, v174
	v_pk_mul_f32 v[230:231], v[180:181], v[184:185]
	v_pk_add_f32 v[180:181], v[86:87], v[162:163]
	v_pk_add_f32 v[184:185], v[54:55], v[166:167]
	v_cvt_pk_u8_f32 v174, v174, 0, 0
	v_rndne_f32_e32 v175, v175
	v_pk_add_f32 v[178:179], v[96:97], v[164:165]
	v_pk_add_f32 v[182:183], v[64:65], v[168:169]
	v_pk_mul_f32 v[184:185], v[180:181], v[184:185]
	v_pk_add_f32 v[180:181], v[46:47], v[162:163]
	v_pk_add_f32 v[236:237], v[18:19], v[166:167]
	v_pk_add_f32 v[162:163], v[38:39], v[162:163]
	v_pk_add_f32 v[166:167], v[10:11], v[166:167]
	v_cvt_pk_u8_f32 v174, v175, 1, v174
	v_rndne_f32_e32 v175, v176
	v_and_or_b32 v176, v224, 1, v225
	v_pk_mul_f32 v[224:225], v[178:179], v[182:183]
	v_pk_add_f32 v[178:179], v[88:89], v[164:165]
	v_pk_add_f32 v[182:183], v[56:57], v[168:169]
	v_pk_mul_f32 v[166:167], v[162:163], v[166:167]
	v_pk_add_f32 v[162:163], v[66:67], v[130:131]
	v_pk_mul_f32 v[182:183], v[178:179], v[182:183]
	v_pk_add_f32 v[178:179], v[48:49], v[164:165]
	v_pk_add_f32 v[234:235], v[20:21], v[168:169]
	v_pk_add_f32 v[164:165], v[40:41], v[164:165]
	v_pk_add_f32 v[168:169], v[12:13], v[168:169]
	v_exp_f32_e32 v162, v162
	v_exp_f32_e32 v177, v177
	v_pk_mul_f32 v[164:165], v[164:165], v[168:169]
	v_pk_add_f32 v[168:169], v[68:69], v[132:133]
	v_exp_f32_e32 v163, v163
	v_exp_f32_e32 v168, v168
	v_exp_f32_e32 v169, v169
	v_fmamk_f32 v162, v162, 0x3b808081, v223
	v_fmamk_f32 v177, v177, 0x3b808081, v223
	v_rcp_f32_e32 v162, v162
	v_fmamk_f32 v163, v163, 0x3b808081, v223
	v_rcp_f32_e32 v177, v177
	v_rcp_f32_e32 v163, v163
	v_fmamk_f32 v168, v168, 0x3b808081, v223
	v_rcp_f32_e32 v168, v168
	v_fmamk_f32 v169, v169, 0x3b808081, v223
	v_rcp_f32_e32 v169, v169
	v_rndne_f32_e32 v162, v162
	v_cvt_pk_u8_f32 v174, v175, 2, v174
	v_rndne_f32_e32 v175, v177
	v_cvt_pk_u8_f32 v162, v162, 0, 0
	v_rndne_f32_e32 v163, v163
	v_cvt_pk_u8_f32 v228, v175, 3, v174
	v_and_b32_e32 v174, -8, v194
	v_cvt_pk_u8_f32 v162, v163, 1, v162
	v_rndne_f32_e32 v163, v168
	v_add_u32_e32 v174, s33, v174
	v_cvt_pk_u8_f32 v162, v163, 2, v162
	v_rndne_f32_e32 v163, v169
	v_ashrrev_i32_e32 v177, 31, v176
	v_ashrrev_i32_e32 v175, 31, v174
	v_cvt_pk_u8_f32 v229, v163, 3, v162
	v_lshlrev_b64 v[168:169], 10, v[176:177]
	v_lshlrev_b64 v[162:163], 11, v[176:177]
	v_pk_mul_f32 v[178:179], v[178:179], v[234:235]
	v_lshl_add_u64 v[234:235], s[78:79], 0, v[162:163]
	v_lshlrev_b64 v[162:163], 1, v[174:175]
	v_lshl_add_u64 v[168:169], s[76:77], 0, v[168:169]
	v_permlane16_swap_b32_e32 v170, v172
	v_permlane16_swap_b32_e32 v171, v173
	v_permlane16_swap_b32_e32 v228, v229
	v_lshl_add_u64 v[234:235], v[234:235], 0, v[162:163]
	v_lshl_add_u64 v[168:169], v[168:169], 0, v[174:175]
	global_store_dwordx4 v[234:235], v[170:173], off
	global_store_dwordx2 v[168:169], v[228:229], off
	v_pk_fma_f32 v[228:229], v[230:231], v[146:147], v[150:151]
	v_pk_fma_f32 v[172:173], v[224:225], v[148:149], v[152:153]
	v_pk_fma_f32 v[228:229], v[142:143], v[192:193], v[228:229]
	v_pk_fma_f32 v[172:173], v[144:145], v[190:191], v[172:173]
	v_pk_add_f32 v[168:169], v[100:101], v[140:141]
	v_pk_add_f32 v[170:171], v[98:99], v[138:139]
	v_pk_fma_f32 v[172:173], v[136:137], v[186:187], v[172:173]
	v_pk_fma_f32 v[186:187], v[134:135], v[188:189], v[228:229]
	v_pk_mul_f32 v[172:173], v[168:169], v[172:173]
	v_pk_mul_f32 v[168:169], v[170:171], v[186:187]
	v_pk_add_f32 v[170:171], v[58:59], v[130:131]
	v_cvt_pk_bf16_f32 v168, v168, v169
	v_cvt_pk_bf16_f32 v169, v172, v173
	v_pk_add_f32 v[172:173], v[60:61], v[132:133]
	v_exp_f32_e32 v170, v170
	v_exp_f32_e32 v171, v171
	v_exp_f32_e32 v172, v172
	v_exp_f32_e32 v173, v173
	v_fmamk_f32 v170, v170, 0x3b808081, v223
	v_rcp_f32_e32 v170, v170
	v_fmamk_f32 v171, v171, 0x3b808081, v223
	v_rcp_f32_e32 v171, v171
	v_fmamk_f32 v172, v172, 0x3b808081, v223
	v_rcp_f32_e32 v172, v172
	v_fmamk_f32 v173, v173, 0x3b808081, v223
	v_rcp_f32_e32 v173, v173
	v_rndne_f32_e32 v170, v170
	v_cvt_pk_u8_f32 v170, v170, 0, 0
	v_rndne_f32_e32 v171, v171
	v_cvt_pk_u8_f32 v170, v171, 1, v170
	v_rndne_f32_e32 v171, v172
	v_pk_fma_f32 v[188:189], v[182:183], v[148:149], v[152:153]
	v_pk_fma_f32 v[228:229], v[184:185], v[146:147], v[150:151]
	v_cvt_pk_u8_f32 v170, v171, 2, v170
	v_rndne_f32_e32 v171, v173
	v_pk_fma_f32 v[188:189], v[144:145], v[224:225], v[188:189]
	v_pk_fma_f32 v[228:229], v[142:143], v[230:231], v[228:229]
	v_cvt_pk_u8_f32 v172, v171, 3, v170
	v_pk_add_f32 v[170:171], v[92:93], v[140:141]
	v_pk_add_f32 v[186:187], v[90:91], v[138:139]
	v_pk_fma_f32 v[188:189], v[136:137], v[190:191], v[188:189]
	v_pk_fma_f32 v[190:191], v[134:135], v[192:193], v[228:229]
	v_pk_mul_f32 v[188:189], v[170:171], v[188:189]
	v_pk_mul_f32 v[170:171], v[186:187], v[190:191]
	v_pk_add_f32 v[186:187], v[50:51], v[130:131]
	v_cvt_pk_bf16_f32 v170, v170, v171
	v_cvt_pk_bf16_f32 v171, v188, v189
	v_pk_add_f32 v[188:189], v[52:53], v[132:133]
	v_exp_f32_e32 v173, v186
	v_exp_f32_e32 v177, v187
	v_exp_f32_e32 v186, v188
	v_exp_f32_e32 v187, v189
	v_fmamk_f32 v173, v173, 0x3b808081, v223
	v_rcp_f32_e32 v173, v173
	v_fmamk_f32 v177, v177, 0x3b808081, v223
	v_rcp_f32_e32 v177, v177
	v_fmamk_f32 v186, v186, 0x3b808081, v223
	v_rcp_f32_e32 v186, v186
	v_fmamk_f32 v187, v187, 0x3b808081, v223
	v_rcp_f32_e32 v187, v187
	v_rndne_f32_e32 v173, v173
	v_cvt_pk_u8_f32 v173, v173, 0, 0
	v_rndne_f32_e32 v177, v177
	v_cvt_pk_u8_f32 v173, v177, 1, v173
	v_rndne_f32_e32 v177, v186
	v_or_b32_e32 v186, 2, v176
	v_cvt_pk_u8_f32 v173, v177, 2, v173
	v_rndne_f32_e32 v177, v187
	v_ashrrev_i32_e32 v187, 31, v186
	v_lshlrev_b64 v[188:189], 10, v[186:187]
	v_lshlrev_b64 v[186:187], 11, v[186:187]
	v_lshl_add_u64 v[186:187], s[78:79], 0, v[186:187]
	v_pk_mul_f32 v[180:181], v[180:181], v[236:237]
	v_permlane16_swap_b32_e32 v168, v170
	v_permlane16_swap_b32_e32 v169, v171
	v_lshl_add_u64 v[186:187], v[186:187], 0, v[162:163]
	v_cvt_pk_u8_f32 v173, v177, 3, v173
	global_store_dwordx4 v[186:187], v[168:171], off
	v_pk_fma_f32 v[186:187], v[178:179], v[148:149], v[152:153]
	v_permlane16_swap_b32_e32 v172, v173
	v_lshl_add_u64 v[168:169], s[76:77], 0, v[188:189]
	v_pk_fma_f32 v[188:189], v[180:181], v[146:147], v[150:151]
	v_lshl_add_u64 v[168:169], v[168:169], 0, v[174:175]
	v_pk_fma_f32 v[186:187], v[144:145], v[182:183], v[186:187]
	v_pk_fma_f32 v[188:189], v[142:143], v[184:185], v[188:189]
	global_store_dwordx2 v[168:169], v[172:173], off
	v_pk_add_f32 v[168:169], v[80:81], v[140:141]
	v_pk_add_f32 v[170:171], v[78:79], v[138:139]
	v_pk_fma_f32 v[186:187], v[136:137], v[224:225], v[186:187]
	v_pk_fma_f32 v[188:189], v[134:135], v[230:231], v[188:189]
	v_pk_mul_f32 v[186:187], v[168:169], v[186:187]
	v_pk_mul_f32 v[168:169], v[170:171], v[188:189]
	v_pk_add_f32 v[170:171], v[14:15], v[130:131]
	v_cvt_pk_bf16_f32 v168, v168, v169
	v_cvt_pk_bf16_f32 v169, v186, v187
	v_pk_add_f32 v[186:187], v[16:17], v[132:133]
	v_exp_f32_e32 v170, v170
	v_exp_f32_e32 v171, v171
	v_exp_f32_e32 v173, v186
	v_exp_f32_e32 v177, v187
	v_fmamk_f32 v170, v170, 0x3b808081, v223
	v_rcp_f32_e32 v170, v170
	v_fmamk_f32 v171, v171, 0x3b808081, v223
	v_rcp_f32_e32 v171, v171
	v_fmamk_f32 v173, v173, 0x3b808081, v223
	v_rcp_f32_e32 v173, v173
	v_fmamk_f32 v177, v177, 0x3b808081, v223
	v_rcp_f32_e32 v177, v177
	v_rndne_f32_e32 v170, v170
	v_cvt_pk_u8_f32 v170, v170, 0, 0
	v_rndne_f32_e32 v171, v171
	v_cvt_pk_u8_f32 v170, v171, 1, v170
	v_rndne_f32_e32 v171, v173
	v_pk_fma_f32 v[190:191], v[164:165], v[148:149], v[152:153]
	v_pk_fma_f32 v[192:193], v[166:167], v[146:147], v[150:151]
	v_cvt_pk_u8_f32 v170, v171, 2, v170
	v_rndne_f32_e32 v171, v177
	v_pk_fma_f32 v[190:191], v[144:145], v[178:179], v[190:191]
	v_pk_fma_f32 v[192:193], v[142:143], v[180:181], v[192:193]
	v_cvt_pk_u8_f32 v186, v171, 3, v170
	v_pk_add_f32 v[170:171], v[44:45], v[140:141]
	v_pk_add_f32 v[188:189], v[42:43], v[138:139]
	v_pk_fma_f32 v[182:183], v[136:137], v[182:183], v[190:191]
	v_pk_fma_f32 v[184:185], v[134:135], v[184:185], v[192:193]
	v_pk_mul_f32 v[182:183], v[170:171], v[182:183]
	v_pk_mul_f32 v[170:171], v[188:189], v[184:185]
	v_pk_add_f32 v[184:185], v[8:9], v[132:133]
	v_cvt_pk_bf16_f32 v170, v170, v171
	v_cvt_pk_bf16_f32 v171, v182, v183
	v_pk_add_f32 v[182:183], v[6:7], v[130:131]
	v_or_b32_e32 v172, 4, v176
	v_exp_f32_e32 v173, v182
	v_exp_f32_e32 v177, v183
	v_exp_f32_e32 v182, v184
	v_exp_f32_e32 v183, v185
	v_fmamk_f32 v173, v173, 0x3b808081, v223
	v_rcp_f32_e32 v173, v173
	v_fmamk_f32 v177, v177, 0x3b808081, v223
	v_rcp_f32_e32 v177, v177
	v_fmamk_f32 v182, v182, 0x3b808081, v223
	v_rcp_f32_e32 v182, v182
	v_fmamk_f32 v183, v183, 0x3b808081, v223
	v_rcp_f32_e32 v183, v183
	v_rndne_f32_e32 v173, v173
	v_cvt_pk_u8_f32 v173, v173, 0, 0
	v_rndne_f32_e32 v177, v177
	v_cvt_pk_u8_f32 v173, v177, 1, v173
	v_rndne_f32_e32 v177, v182
	v_cvt_pk_u8_f32 v173, v177, 2, v173
	v_rndne_f32_e32 v177, v183
	v_cvt_pk_u8_f32 v187, v177, 3, v173
	v_ashrrev_i32_e32 v173, 31, v172
	v_lshlrev_b64 v[182:183], 10, v[172:173]
	v_lshlrev_b64 v[172:173], 11, v[172:173]
	v_lshl_add_u64 v[172:173], s[78:79], 0, v[172:173]
	v_permlane16_swap_b32_e32 v168, v170
	v_permlane16_swap_b32_e32 v169, v171
	v_lshl_add_u64 v[172:173], v[172:173], 0, v[162:163]
	global_store_dwordx4 v[172:173], v[168:171], off
	v_pk_fma_f32 v[172:173], v[156:157], v[148:149], v[152:153]
	v_permlane16_swap_b32_e32 v186, v187
	v_lshl_add_u64 v[168:169], s[76:77], 0, v[182:183]
	v_pk_fma_f32 v[182:183], v[154:155], v[146:147], v[150:151]
	v_lshl_add_u64 v[168:169], v[168:169], 0, v[174:175]
	v_pk_fma_f32 v[172:173], v[144:145], v[164:165], v[172:173]
	v_pk_fma_f32 v[182:183], v[142:143], v[166:167], v[182:183]
	global_store_dwordx2 v[168:169], v[186:187], off
	v_pk_add_f32 v[168:169], v[36:37], v[140:141]
	v_pk_add_f32 v[170:171], v[34:35], v[138:139]
	v_pk_fma_f32 v[172:173], v[136:137], v[178:179], v[172:173]
	v_pk_fma_f32 v[178:179], v[134:135], v[180:181], v[182:183]
	v_pk_mul_f32 v[172:173], v[168:169], v[172:173]
	v_pk_mul_f32 v[168:169], v[170:171], v[178:179]
	v_pk_add_f32 v[170:171], v[126:127], v[130:131]
	v_pk_add_f32 v[130:131], v[118:119], v[130:131]
	v_cvt_pk_bf16_f32 v168, v168, v169
	v_cvt_pk_bf16_f32 v169, v172, v173
	v_exp_f32_e32 v170, v170
	v_exp_f32_e32 v130, v130
	v_pk_add_f32 v[172:173], v[128:129], v[132:133]
	v_pk_add_f32 v[132:133], v[120:121], v[132:133]
	v_exp_f32_e32 v131, v131
	v_exp_f32_e32 v171, v171
	v_exp_f32_e32 v132, v132
	v_exp_f32_e32 v172, v172
	v_exp_f32_e32 v133, v133
	v_exp_f32_e32 v173, v173
	v_fmamk_f32 v130, v130, 0x3b808081, v223
	v_fmamk_f32 v170, v170, 0x3b808081, v223
	v_rcp_f32_e32 v130, v130
	v_fmamk_f32 v131, v131, 0x3b808081, v223
	v_rcp_f32_e32 v170, v170
	v_fmamk_f32 v171, v171, 0x3b808081, v223
	v_rcp_f32_e32 v131, v131
	v_fmamk_f32 v132, v132, 0x3b808081, v223
	v_rcp_f32_e32 v171, v171
	v_fmamk_f32 v172, v172, 0x3b808081, v223
	v_rcp_f32_e32 v132, v132
	v_fmamk_f32 v133, v133, 0x3b808081, v223
	v_rcp_f32_e32 v172, v172
	v_fmamk_f32 v173, v173, 0x3b808081, v223
	v_rcp_f32_e32 v133, v133
	v_rcp_f32_e32 v173, v173
	v_rndne_f32_e32 v130, v130
	v_rndne_f32_e32 v170, v170
	v_cvt_pk_u8_f32 v130, v130, 0, 0
	v_rndne_f32_e32 v131, v131
	v_cvt_pk_u8_f32 v170, v170, 0, 0
	v_rndne_f32_e32 v171, v171
	v_cvt_pk_u8_f32 v130, v131, 1, v130
	v_rndne_f32_e32 v131, v132
	v_cvt_pk_u8_f32 v170, v171, 1, v170
	v_rndne_f32_e32 v171, v172
	v_cvt_pk_u8_f32 v130, v131, 2, v130
	v_rndne_f32_e32 v131, v133
	v_cvt_pk_u8_f32 v170, v171, 2, v170
	v_rndne_f32_e32 v171, v173
	v_pk_fma_f32 v[148:149], v[160:161], v[148:149], v[152:153]
	v_pk_fma_f32 v[146:147], v[158:159], v[146:147], v[150:151]
	v_cvt_pk_u8_f32 v173, v131, 3, v130
	v_or_b32_e32 v130, 6, v176
	v_pk_fma_f32 v[144:145], v[144:145], v[156:157], v[148:149]
	v_pk_fma_f32 v[142:143], v[142:143], v[154:155], v[146:147]
	v_ashrrev_i32_e32 v131, 31, v130
	v_pk_add_f32 v[140:141], v[28:29], v[140:141]
	v_pk_add_f32 v[138:139], v[26:27], v[138:139]
	v_pk_fma_f32 v[136:137], v[136:137], v[164:165], v[144:145]
	v_pk_fma_f32 v[134:135], v[134:135], v[166:167], v[142:143]
	v_lshlrev_b64 v[132:133], 10, v[130:131]
	v_lshlrev_b64 v[130:131], 11, v[130:131]
	v_cvt_pk_u8_f32 v172, v171, 3, v170
	v_pk_mul_f32 v[136:137], v[140:141], v[136:137]
	v_pk_mul_f32 v[134:135], v[138:139], v[134:135]
	v_lshl_add_u64 v[130:131], s[78:79], 0, v[130:131]
	v_cvt_pk_bf16_f32 v170, v134, v135
	v_cvt_pk_bf16_f32 v171, v136, v137
	v_lshl_add_u64 v[130:131], v[130:131], 0, v[162:163]
	v_permlane16_swap_b32_e32 v168, v170
	v_permlane16_swap_b32_e32 v169, v171
	global_store_dwordx4 v[130:131], v[168:171], off
	v_lshl_add_u64 v[130:131], s[76:77], 0, v[132:133]
	v_permlane16_swap_b32_e32 v172, v173
	v_lshl_add_u64 v[130:131], v[130:131], 0, v[174:175]
	global_store_dwordx2 v[130:131], v[172:173], off
	s_andn2_b64 vcc, exec, s[2:3]
	s_mov_b64 s[2:3], -1
	s_cbranch_vccnz .LBB0_217

	.amdhsa_kernel _Z14fwd_megakernel4Args
		.amdhsa_group_segment_fixed_size 0
		.amdhsa_private_segment_fixed_size 0
		.amdhsa_kernarg_size 456
		.amdhsa_user_sgpr_count 2
		.amdhsa_user_sgpr_dispatch_ptr 0
		.amdhsa_user_sgpr_queue_ptr 0
		.amdhsa_user_sgpr_kernarg_segment_ptr 1
		.amdhsa_user_sgpr_dispatch_id 0
		.amdhsa_user_sgpr_kernarg_preload_length 0
		.amdhsa_user_sgpr_kernarg_preload_offset 0
		.amdhsa_user_sgpr_private_segment_size 0
		.amdhsa_uses_dynamic_stack 0
		.amdhsa_enable_private_segment 0
		.amdhsa_system_sgpr_workgroup_id_x 1
		.amdhsa_system_sgpr_workgroup_id_y 0
		.amdhsa_system_sgpr_workgroup_id_z 0
		.amdhsa_system_sgpr_workgroup_info 0
		.amdhsa_system_vgpr_workitem_id 0
		.amdhsa_next_free_vgpr 253
		.amdhsa_next_free_sgpr 102
		.amdhsa_accum_offset 256
		.amdhsa_reserve_vcc 1
		.amdhsa_float_round_mode_32 0
		.amdhsa_float_round_mode_16_64 0
		.amdhsa_float_denorm_mode_32 3
		.amdhsa_float_denorm_mode_16_64 3
		.amdhsa_dx10_clamp 1
		.amdhsa_ieee_mode 1
		.amdhsa_fp16_overflow 0
		.amdhsa_tg_split 0
		.amdhsa_exception_fp_ieee_invalid_op 0
		.amdhsa_exception_fp_denorm_src 0
		.amdhsa_exception_fp_ieee_div_zero 0
		.amdhsa_exception_fp_ieee_overflow 0
		.amdhsa_exception_fp_ieee_underflow 0
		.amdhsa_exception_fp_ieee_inexact 0
		.amdhsa_exception_int_div_zero 0
	.end_amdhsa_kernel

amdhsa.kernels:
  - .agpr_count:     0
    .args:
      - .offset:         0
        .size:           200
        .value_kind:     by_value
      - .offset:         200
        .size:           4
        .value_kind:     hidden_block_count_x
      - .offset:         204
        .size:           4
        .value_kind:     hidden_block_count_y
      - .offset:         208
        .size:           4
        .value_kind:     hidden_block_count_z
      - .offset:         212
        .size:           2
        .value_kind:     hidden_group_size_x
      - .offset:         214
        .size:           2
        .value_kind:     hidden_group_size_y
      - .offset:         216
        .size:           2
        .value_kind:     hidden_group_size_z
      - .offset:         218
        .size:           2
        .value_kind:     hidden_remainder_x
      - .offset:         220
        .size:           2
        .value_kind:     hidden_remainder_y
      - .offset:         222
        .size:           2
        .value_kind:     hidden_remainder_z
      - .offset:         240
        .size:           8
        .value_kind:     hidden_global_offset_x
      - .offset:         248
        .size:           8
        .value_kind:     hidden_global_offset_y
      - .offset:         256
        .size:           8
        .value_kind:     hidden_global_offset_z
      - .offset:         264
        .size:           2
        .value_kind:     hidden_grid_dims
      - .offset:         320
        .size:           4
        .value_kind:     hidden_dynamic_lds_size
    .group_segment_fixed_size: 0
    .kernarg_segment_align: 8
    .kernarg_segment_size: 456
    .language:       OpenCL C
    .language_version:
      - 2
      - 0
    .max_flat_workgroup_size: 512
    .name:           _Z14fwd_megakernel4Args
    .private_segment_fixed_size: 0
    .sgpr_count:     108
    .sgpr_spill_count: 64
    .symbol:         _Z14fwd_megakernel4Args.kd
    .uniform_work_group_size: 1
    .uses_dynamic_stack: false
    .vgpr_count:     253
    .vgpr_spill_count: 0
    .wavefront_size: 64
